# PH1 rebalanced: the four workgroups that take two adaLN steps skip weight copies; 16 fold-GEMM workgroups take those 128 items (one per wave)
# speedup vs baseline: 1.0111x; 1.0064x over previous
.LBB0_1300:
	s_andn2_b64 vcc, exec, s[0:1]
	s_cbranch_vccnz .LBB0_1329
	s_movk_i32 s98, 0xb1f
	s_sub_i32 s0, s96, 8
	s_cmp_lt_u32 s0, 4
	s_cbranch_scc1 .LBB0_1329
	s_and_b64 vcc, exec, s[30:31]
	s_cbranch_vccnz .LBB0_1329
	s_cmp_lt_i32 s26, 32
	s_cbranch_scc0 .Lw_normal
	s_lshl_b32 s0, s26, 3
	s_add_i32 s0, s0, s86
	s_cmp_gt_u32 s0, 0x7f
	s_cbranch_scc1 .LBB0_1329
	s_and_b32 s9, s0, 31
	s_add_i32 s9, s9, 32
	s_lshr_b32 s0, s0, 5
	s_mul_i32 s0, s0, 0x4e0
	s_add_i32 s9, s9, s0
	s_mov_b32 s98, -1
	s_branch .Lw_go
.Lw_normal:
	s_cmpk_lt_i32 s96, 0x80
	s_cselect_b32 s0, -4, 0xffffffdc
	s_add_i32 s0, s0, s96
	s_lshl_b32 s0, s0, 3
	s_add_i32 s9, s86, s0
	s_cmpk_gt_i32 s9, 0xfff
	s_cbranch_scc1 .LBB0_1329
.Lw_go:
	v_lshlrev_b32_e32 v0, 2, v4
	s_waitcnt lgkmcnt(0)
	v_ashrrev_i32_e32 v5, 3, v4
	v_and_b32_e32 v0, 28, v0
	s_movk_i32 s0, 0x84
	v_lshlrev_b32_e32 v2, 3, v4
	v_lshl_add_u32 v3, v0, 2, s8
	v_mul_lo_u32 v6, v5, s0
	v_and_b32_e32 v2, 56, v2
	v_mov_b32_e32 v1, 0
	v_mul_u32_u24_e32 v4, 0x84, v2
	v_lshlrev_b32_e32 v7, 2, v5
	v_add_u32_e32 v6, v3, v6
	v_add3_u32 v4, s8, v4, v7
	v_lshlrev_b32_e32 v0, 2, v0
	v_add_u32_e32 v7, 0x420, v6
	v_add_u32_e32 v8, 0x428, v6
	v_add_u32_e32 v9, 0x840, v6
	v_add_u32_e32 v10, 0x848, v6
	v_add_u32_e32 v11, 0xc60, v6
	v_add_u32_e32 v12, 0xc68, v6
	v_add_u32_e32 v13, 0x1080, v6
	v_add_u32_e32 v14, 0x1088, v6
	v_add_u32_e32 v15, 0x14a0, v6
	v_add_u32_e32 v16, 0x14a8, v6
	v_add_u32_e32 v17, 0x18c0, v6
	v_add_u32_e32 v18, 0x18c8, v6
	v_add_u32_e32 v19, 0x1ce0, v6
	v_add_u32_e32 v20, 0x1ce8, v6
	v_lshlrev_b32_e32 v2, 1, v2
	v_mov_b32_e32 v3, v1
	s_movk_i32 s8, 0x7fff
	s_mov_b32 s10, 0xffff0000
	s_branch .LBB0_1306

.LBB0_1305:
	s_add_u32 s14, s50, s4
	s_addc_u32 s15, s51, s5
	s_lshr_b32 s4, s11, 5
	v_cvt_f32_u32_e32 v21, s4
	s_sub_i32 s7, 0, s4
	s_abs_i32 s6, s12
	s_ashr_i32 s5, s12, 31
	v_rcp_iflag_f32_e32 v21, v21
	s_nop 0
	v_mul_f32_e32 v21, 0x4f7ffffe, v21
	v_cvt_u32_f32_e32 v21, v21
	s_nop 0
	v_readfirstlane_b32 s13, v21
	s_mul_i32 s7, s7, s13
	s_mul_hi_u32 s7, s13, s7
	s_add_i32 s13, s13, s7
	s_mul_hi_u32 s7, s6, s13
	s_mul_i32 s13, s7, s4
	s_sub_i32 s6, s6, s13
	s_add_i32 s16, s7, 1
	s_sub_i32 s13, s6, s4
	s_cmp_ge_u32 s6, s4
	s_cselect_b32 s7, s16, s7
	s_cselect_b32 s6, s13, s6
	s_add_i32 s13, s7, 1
	s_cmp_ge_u32 s6, s4
	s_cselect_b32 s6, s13, s7
	s_xor_b32 s6, s6, s5
	s_sub_i32 s5, s6, s5
	s_mul_i32 s4, s5, s4
	s_sub_i32 s4, s12, s4
	s_lshl_b32 s4, s4, 5
	s_lshl_b32 s6, s5, 6
	s_ashr_i32 s5, s4, 31
	s_lshl_b64 s[12:13], s[4:5], 2
	v_add_u32_e32 v21, s6, v5
	s_add_u32 s2, s2, s12
	s_addc_u32 s3, s3, s13
	v_add_u32_e32 v30, 16, v21
	v_add_u32_e32 v38, 32, v21
	v_lshl_add_u64 v[50:51], s[2:3], 0, v[0:1]
	v_mad_u64_u32 v[22:23], s[2:3], v21, s11, 0
	v_ashrrev_i32_e32 v33, 31, v30
	v_mad_u64_u32 v[30:31], s[2:3], v30, s11, 0
	v_ashrrev_i32_e32 v41, 31, v38
	v_mad_u64_u32 v[38:39], s[2:3], v38, s11, 0
	v_ashrrev_i32_e32 v25, 31, v21
	v_mov_b32_e32 v24, v23
	v_mov_b32_e32 v32, v31
	v_mov_b32_e32 v40, v39
	v_mad_u64_u32 v[24:25], s[2:3], v25, s11, v[24:25]
	v_mad_u64_u32 v[32:33], s[2:3], v33, s11, v[32:33]
	v_mad_u64_u32 v[40:41], s[2:3], v41, s11, v[40:41]
	v_mov_b32_e32 v23, v24
	v_add_u32_e32 v24, 8, v21
	v_mov_b32_e32 v31, v32
	v_add_u32_e32 v32, 24, v21
	v_mov_b32_e32 v39, v40
	v_add_u32_e32 v40, 40, v21
	v_ashrrev_i32_e32 v27, 31, v24
	v_mad_u64_u32 v[24:25], s[2:3], v24, s11, 0
	v_ashrrev_i32_e32 v35, 31, v32
	v_mad_u64_u32 v[32:33], s[2:3], v32, s11, 0
	v_ashrrev_i32_e32 v43, 31, v40
	v_mad_u64_u32 v[40:41], s[2:3], v40, s11, 0
	v_mov_b32_e32 v26, v25
	v_mov_b32_e32 v34, v33
	v_mov_b32_e32 v42, v41
	v_mad_u64_u32 v[26:27], s[2:3], v27, s11, v[26:27]
	v_mad_u64_u32 v[34:35], s[2:3], v35, s11, v[34:35]
	v_mad_u64_u32 v[42:43], s[2:3], v43, s11, v[42:43]
	v_mov_b32_e32 v25, v26
	v_mov_b32_e32 v33, v34
	v_mov_b32_e32 v41, v42
	v_lshl_add_u64 v[22:23], v[22:23], 2, v[50:51]
	v_lshl_add_u64 v[26:27], v[24:25], 2, v[50:51]
	v_lshl_add_u64 v[30:31], v[30:31], 2, v[50:51]
	v_lshl_add_u64 v[34:35], v[32:33], 2, v[50:51]
	v_lshl_add_u64 v[38:39], v[38:39], 2, v[50:51]
	v_lshl_add_u64 v[42:43], v[40:41], 2, v[50:51]
	global_load_dwordx4 v[22:25], v[22:23], off
	s_nop 0
	global_load_dwordx4 v[26:29], v[26:27], off
	s_nop 0
	global_load_dwordx4 v[30:33], v[30:31], off
	s_nop 0
	global_load_dwordx4 v[34:37], v[34:35], off
	s_nop 0
	global_load_dwordx4 v[38:41], v[38:39], off
	s_nop 0
	global_load_dwordx4 v[42:45], v[42:43], off
	v_add_u32_e32 v46, 48, v21
	v_ashrrev_i32_e32 v49, 31, v46
	v_mad_u64_u32 v[46:47], s[2:3], v46, s11, 0
	v_mov_b32_e32 v48, v47
	v_add_u32_e32 v21, 56, v21
	v_mad_u64_u32 v[48:49], s[2:3], v49, s11, v[48:49]
	v_mad_u64_u32 v[52:53], s[2:3], v21, s11, 0
	v_mov_b32_e32 v47, v48
	v_ashrrev_i32_e32 v55, 31, v21
	v_mov_b32_e32 v54, v53
	v_lshl_add_u64 v[46:47], v[46:47], 2, v[50:51]
	v_mad_u64_u32 v[54:55], s[2:3], v55, s11, v[54:55]
	global_load_dwordx4 v[46:49], v[46:47], off
	v_mov_b32_e32 v53, v54
	v_lshl_add_u64 v[50:51], v[52:53], 2, v[50:51]
	global_load_dwordx4 v[50:53], v[50:51], off
	s_ashr_i32 s7, s6, 31
	s_lshl_b64 s[2:3], s[6:7], 1
	s_add_u32 s2, s14, s2
	s_addc_u32 s3, s15, s3
	s_waitcnt vmcnt(0)
	ds_write2_b32 v6, v22, v23 offset1:1
	ds_write2_b32 v6, v24, v25 offset0:2 offset1:3
	ds_write2_b32 v7, v26, v27 offset1:1
	ds_write2_b32 v8, v28, v29 offset1:1
	ds_write2_b32 v9, v30, v31 offset1:1
	ds_write2_b32 v10, v32, v33 offset1:1
	ds_write2_b32 v11, v34, v35 offset1:1
	ds_write2_b32 v12, v36, v37 offset1:1
	ds_write2_b32 v13, v38, v39 offset1:1
	ds_write2_b32 v14, v40, v41 offset1:1
	ds_write2_b32 v15, v42, v43 offset1:1
	ds_write2_b32 v16, v44, v45 offset1:1
	ds_write2_b32 v17, v46, v47 offset1:1
	ds_write2_b32 v18, v48, v49 offset1:1
	ds_write2_b32 v19, v50, v51 offset1:1
	ds_write2_b32 v20, v52, v53 offset1:1
	s_waitcnt lgkmcnt(0)
	ds_read2_b32 v[26:27], v4 offset1:8
	ds_read2_b32 v[30:31], v4 offset0:33 offset1:41
	ds_read2_b32 v[32:33], v4 offset0:66 offset1:74
	ds_read2_b32 v[34:35], v4 offset0:99 offset1:107
	ds_read2_b32 v[36:37], v4 offset0:132 offset1:140
	s_waitcnt lgkmcnt(4)
	v_bfe_u32 v21, v26, 16, 1
	v_add3_u32 v21, v26, v21, s8
	s_waitcnt lgkmcnt(3)
	v_bfe_u32 v22, v30, 16, 1
	v_lshrrev_b32_e32 v21, 16, v21
	v_add3_u32 v22, v30, v22, s8
	ds_read2_b32 v[38:39], v4 offset0:165 offset1:173
	v_and_or_b32 v22, v22, s10, v21
	s_waitcnt lgkmcnt(3)
	v_bfe_u32 v21, v32, 16, 1
	v_add3_u32 v21, v32, v21, s8
	s_waitcnt lgkmcnt(2)
	v_bfe_u32 v23, v34, 16, 1
	ds_read2_b32 v[40:41], v4 offset0:198 offset1:206
	v_lshrrev_b32_e32 v21, 16, v21
	v_add3_u32 v23, v34, v23, s8
	ds_read2_b32 v[42:43], v4 offset0:231 offset1:239
	v_and_or_b32 v23, v23, s10, v21
	s_waitcnt lgkmcnt(3)
	v_bfe_u32 v21, v36, 16, 1
	v_add3_u32 v21, v36, v21, s8
	s_waitcnt lgkmcnt(2)
	v_bfe_u32 v24, v38, 16, 1
	v_lshrrev_b32_e32 v21, 16, v21
	v_add3_u32 v24, v38, v24, s8
	v_and_or_b32 v24, v24, s10, v21
	s_waitcnt lgkmcnt(1)
	v_bfe_u32 v21, v40, 16, 1
	v_add3_u32 v21, v40, v21, s8
	s_waitcnt lgkmcnt(0)
	v_bfe_u32 v25, v42, 16, 1
	v_lshrrev_b32_e32 v21, 16, v21
	v_add3_u32 v25, v42, v25, s8
	v_and_or_b32 v25, v25, s10, v21
	v_add_u32_e32 v21, s4, v5
	v_ashrrev_i32_e32 v26, 31, v21
	v_lshl_add_u64 v[28:29], s[2:3], 0, v[2:3]
	v_mul_lo_u32 v26, s0, v26
	v_mul_lo_u32 v30, s1, v21
	v_mad_u64_u32 v[44:45], s[2:3], s0, v21, 0
	v_add3_u32 v45, v45, v26, v30
	v_lshl_add_u64 v[44:45], v[44:45], 1, v[28:29]
	global_store_dwordx4 v[44:45], v[22:25], off
	v_bfe_u32 v26, v43, 16, 1
	v_add3_u32 v26, v43, v26, s8
	v_bfe_u32 v22, v27, 16, 1
	v_add3_u32 v22, v27, v22, s8
	v_bfe_u32 v23, v31, 16, 1
	v_lshrrev_b32_e32 v22, 16, v22
	v_add3_u32 v23, v31, v23, s8
	v_and_or_b32 v22, v23, s10, v22
	v_bfe_u32 v23, v33, 16, 1
	v_add3_u32 v23, v33, v23, s8
	v_bfe_u32 v24, v35, 16, 1
	v_lshrrev_b32_e32 v23, 16, v23
	v_add3_u32 v24, v35, v24, s8
	v_and_or_b32 v23, v24, s10, v23
	v_bfe_u32 v24, v37, 16, 1
	v_add3_u32 v24, v37, v24, s8
	v_bfe_u32 v25, v39, 16, 1
	v_lshrrev_b32_e32 v24, 16, v24
	v_add3_u32 v25, v39, v25, s8
	v_and_or_b32 v24, v25, s10, v24
	v_bfe_u32 v25, v41, 16, 1
	v_add3_u32 v25, v41, v25, s8
	v_lshrrev_b32_e32 v25, 16, v25
	v_and_or_b32 v25, v26, s10, v25
	v_add_u32_e32 v26, 8, v21
	v_ashrrev_i32_e32 v27, 31, v26
	v_mul_lo_u32 v32, s0, v27
	v_mul_lo_u32 v33, s1, v26
	v_mad_u64_u32 v[26:27], s[2:3], s0, v26, 0
	v_add3_u32 v27, v27, v32, v33
	ds_read2_b32 v[30:31], v4 offset0:16 offset1:24
	v_lshl_add_u64 v[26:27], v[26:27], 1, v[28:29]
	global_store_dwordx4 v[26:27], v[22:25], off
	ds_read2_b32 v[26:27], v4 offset0:49 offset1:57
	ds_read2_b32 v[32:33], v4 offset0:82 offset1:90
	ds_read2_b32 v[34:35], v4 offset0:115 offset1:123
	s_waitcnt lgkmcnt(3)
	v_bfe_u32 v22, v30, 16, 1
	v_add3_u32 v22, v30, v22, s8
	s_waitcnt lgkmcnt(2)
	v_bfe_u32 v23, v26, 16, 1
	ds_read2_b32 v[36:37], v4 offset0:148 offset1:156
	v_lshrrev_b32_e32 v22, 16, v22
	v_add3_u32 v23, v26, v23, s8
	ds_read2_b32 v[38:39], v4 offset0:181 offset1:189
	v_and_or_b32 v22, v23, s10, v22
	s_waitcnt lgkmcnt(3)
	v_bfe_u32 v23, v32, 16, 1
	v_add3_u32 v23, v32, v23, s8
	s_waitcnt lgkmcnt(2)
	v_bfe_u32 v24, v34, 16, 1
	ds_read2_b32 v[40:41], v4 offset0:214 offset1:222
	v_lshrrev_b32_e32 v23, 16, v23
	v_add3_u32 v24, v34, v24, s8
	ds_read2_b32 v[42:43], v4 offset0:247 offset1:255
	v_and_or_b32 v23, v24, s10, v23
	s_waitcnt lgkmcnt(3)
	v_bfe_u32 v24, v36, 16, 1
	v_add3_u32 v24, v36, v24, s8
	s_waitcnt lgkmcnt(2)
	v_bfe_u32 v25, v38, 16, 1
	v_lshrrev_b32_e32 v24, 16, v24
	v_add3_u32 v25, v38, v25, s8
	v_and_or_b32 v24, v25, s10, v24
	s_waitcnt lgkmcnt(1)
	v_bfe_u32 v25, v40, 16, 1
	v_add3_u32 v25, v40, v25, s8
	s_waitcnt lgkmcnt(0)
	v_bfe_u32 v26, v42, 16, 1
	v_lshrrev_b32_e32 v25, 16, v25
	v_add3_u32 v26, v42, v26, s8
	v_and_or_b32 v25, v26, s10, v25
	v_add_u32_e32 v26, 16, v21
	v_ashrrev_i32_e32 v30, 31, v26
	v_mul_lo_u32 v30, s0, v30
	v_mul_lo_u32 v32, s1, v26
	v_mad_u64_u32 v[44:45], s[2:3], s0, v26, 0
	v_add3_u32 v45, v45, v30, v32
	v_lshl_add_u64 v[44:45], v[44:45], 1, v[28:29]
	global_store_dwordx4 v[44:45], v[22:25], off
	v_bfe_u32 v26, v43, 16, 1
	v_add3_u32 v26, v43, v26, s8
	v_bfe_u32 v22, v31, 16, 1
	v_add3_u32 v22, v31, v22, s8
	v_bfe_u32 v23, v27, 16, 1
	v_lshrrev_b32_e32 v22, 16, v22
	v_add3_u32 v23, v27, v23, s8
	v_and_or_b32 v22, v23, s10, v22
	v_bfe_u32 v23, v33, 16, 1
	v_add3_u32 v23, v33, v23, s8
	v_bfe_u32 v24, v35, 16, 1
	v_lshrrev_b32_e32 v23, 16, v23
	v_add3_u32 v24, v35, v24, s8
	v_and_or_b32 v23, v24, s10, v23
	v_bfe_u32 v24, v37, 16, 1
	v_add3_u32 v24, v37, v24, s8
	v_bfe_u32 v25, v39, 16, 1
	v_lshrrev_b32_e32 v24, 16, v24
	v_add3_u32 v25, v39, v25, s8
	v_and_or_b32 v24, v25, s10, v24
	v_bfe_u32 v25, v41, 16, 1
	v_add3_u32 v25, v41, v25, s8
	v_lshrrev_b32_e32 v25, 16, v25
	v_add_u32_e32 v21, 24, v21
	v_and_or_b32 v25, v26, s10, v25
	v_ashrrev_i32_e32 v26, 31, v21
	v_mul_lo_u32 v30, s0, v26
	v_mul_lo_u32 v31, s1, v21
	v_mad_u64_u32 v[26:27], s[0:1], s0, v21, 0
	v_add3_u32 v27, v27, v30, v31
	v_lshl_add_u64 v[26:27], v[26:27], 1, v[28:29]
	global_store_dwordx4 v[26:27], v[22:25], off
	s_waitcnt lgkmcnt(0)
	s_add_i32 s0, s9, 0x4e0
	s_cmp_gt_i32 s9, s98
	s_mov_b32 s9, s0
	s_cbranch_scc1 .LBB0_1329
